# v86 + Wo/down GEMMs: per-tile s_waitcnt vmcnt(0) (protects phase set-up registers only) taken once at the phase entry
# baseline (speedup 1.0000x reference)
; __device__ __forceinline__ int opaque_tid() { int t = (int)threadIdx.x; asm volatile("" : "+v"(t)); return t; }
; #define PG8_STAGE(bufoff, gbase, voff) do { _Pragma("unroll") for (int _i = 0; _i < 2; ++_i) \
;         __builtin_amdgcn_global_load_lds((const unsigned*)((const char*)(gbase) + (voff)[_i]), (PG8_LAS unsigned*)(lds + (bufoff) + ldsw + _i * 8192), 16, 0, 0); } while (0)
; #define PG8_WAIT_V(n) asm volatile("s_waitcnt vmcnt(" #n ")" ::: "memory")
; #define PG8_BAR __builtin_amdgcn_s_barrier()
; template <class Epi, class Sched, bool ALIGN_EPI = false, bool SP2 = false>
; __device__ __forceinline__ void gemm_phase(PG8_LAS unsigned char* lds, const Gemm g, const Sched& S, const Epi& E) {
;     const int tid = opaque_tid(), wid = __builtin_amdgcn_readfirstlane(tid >> 6), lane = tid & 63, wr = wid >> 2, wc = wid & 3, fr = lane & 15, fq = lane >> 4;
;     const int K = g.K, nt = K / BK;
;     unsigned voffA[2], voffB[2];
; #pragma unroll
;     for (int i = 0; i < 2; ++i) { int R, C; stage_rc(tid * 16 + i * 8192, R, C); const int Rb = Epi::PERM ? ((R & ~31) + perm32(R & 31)) : R;
;         voffA[i] = (unsigned)(R * K + C) * 2u; voffB[i] = (unsigned)(Rb * K + C) * 2u; }
;     const size_t kstep = (size_t)(BK * 2);
;     const size_t hstep = (size_t)HALF * K * 2;
;     const size_t tstep = 2 * hstep;
;     const unsigned ldsw = (unsigned)wid * 1024u;
;     const int aoff = lds_byte(wr * 64 + fr, fq * 8), boff = lds_byte(wc * 32 + fr, fq * 8);
;     ...
;         PG8_STAGE(PG8_SB(1, 0), cB + kstep, voffB); PG8_STAGE(PG8_SA(1, 0), cA + kstep, voffA); PG8_STAGE(PG8_SB(1, 1), cB + hstep + kstep, voffB);
;         PG8_WAIT_V(6); PG8_BAR;
.LBB0_319:
	s_add_u32 s10, s4, 0x6400000
	s_addc_u32 s11, s5, 0
	s_add_u32 s12, s4, 0x1a600000
	s_addc_u32 s13, s5, 0
	s_and_b32 s48, s6, 3
	s_add_i32 m0, s42, 0x18000
	v_lshl_add_u64 v[10:11], v[10:11], 0, s[82:83]
	s_lshl_b32 s6, s7, 13
	s_lshl_b32 s14, s48, 12
	s_waitcnt vmcnt(2)
	s_barrier
	global_load_lds_dwordx4 v[10:11], off
	v_lshl_add_u64 v[8:9], v[8:9], 0, s[82:83]
	s_add_i32 m0, s42, 0x1a000
	s_add_i32 s49, s42, 0x8000
	s_add_i32 s50, s42, 0xa000
	global_load_lds_dwordx4 v[8:9], off
	v_lshl_add_u64 v[4:5], v[4:5], 0, s[82:83]
	s_mov_b32 m0, s49
	s_add_u32 s4, s30, 0x40080
	global_load_lds_dwordx4 v[4:5], off
	v_lshl_add_u64 v[4:5], v[6:7], 0, s[82:83]
	s_mov_b32 m0, s50
	s_addc_u32 s5, s31, 0
	global_load_lds_dwordx4 v[4:5], off
	s_add_i32 m0, s42, 0x1c000
	v_lshl_add_u64 v[4:5], s[4:5], 0, v[202:203]
	global_load_lds_dwordx4 v[4:5], off
	v_lshl_add_u64 v[4:5], s[4:5], 0, v[206:207]
	s_add_i32 m0, s42, 0x1e000
	s_cmpk_lt_u32 s3, 0x100
	global_load_lds_dwordx4 v[4:5], off
	v_bfe_u32 v4, v12, 4, 2
	v_and_b32_e32 v5, 15, v12
	v_lshlrev_b32_e32 v7, 4, v4
	v_lshl_or_b32 v3, s7, 6, v5
	v_lshlrev_b32_e32 v6, 3, v4
	v_lshl_or_b32 v5, v5, 6, v7
	v_lshlrev_b32_e32 v7, 2, v12
	v_cmp_eq_u32_e64 s[4:5], 0, v4
	v_lshlrev_b32_e32 v4, 14, v13
	v_and_b32_e32 v7, 32, v7
	v_and_b32_e32 v4, 0xffff8000, v4
	v_bitop3_b32 v8, v5, s6, v7 bitop3:0xde
	v_bitop3_b32 v251, v5, s14, v7 bitop3:0xde
	v_add_u32_e32 v251, 0x10000, v251
	v_lshl_add_u32 v4, v14, 11, v4
	v_and_b32_e32 v5, 1, v13
	v_lshl_or_b32 v4, v5, 6, v4
	v_lshl_add_u32 v208, v15, 1, v4
	v_lshlrev_b32_e32 v4, 14, v16
	v_and_b32_e32 v4, 0xffff8000, v4
	s_waitcnt vmcnt(6)
	v_lshl_add_u32 v4, v17, 11, v4
	v_and_b32_e32 v5, 1, v16
	v_lshl_or_b32 v4, v5, 6, v4
	v_lshl_or_b32 v252, s48, 5, v6
	s_cselect_b64 s[14:15], -1, 0
	s_mov_b32 s72, 0
	s_ashr_i32 s51, s36, 31
	v_mov_b32_e32 v209, v2
	v_lshl_add_u32 v210, v18, 1, v4
	v_mov_b32_e32 v211, v2
	v_add_u32_e32 v253, 0, v8
	s_waitcnt vmcnt(0)
	s_barrier
	s_branch .LBB0_322

; #define PG8_STAGE(bufoff, gbase, voff) do { _Pragma("unroll") for (int _i = 0; _i < 2; ++_i) \
;         __builtin_amdgcn_global_load_lds((const unsigned*)((const char*)(gbase) + (voff)[_i]), (PG8_LAS unsigned*)(lds + (bufoff) + ldsw + _i * 8192), 16, 0, 0); } while (0)
; #define PG8_LDA(dst, b, h) do { _Pragma("unroll") for (int m = 0; m < 4; ++m) _Pragma("unroll") for (int k = 0; k < 2; ++k) dst[m][k] = *(const PG8_LAS bf16x8*)(lds + PG8_SA(b, h) + aoff + m * 2048 + k * 1024); } while (0)
; #define PG8_LDB(dst, b, h) do { _Pragma("unroll") for (int n = 0; n < 2; ++n) _Pragma("unroll") for (int k = 0; k < 2; ++k) dst[n][k] = *(const PG8_LAS bf16x8*)(lds + PG8_SB(b, h) + boff + n * 2048 + k * 1024); } while (0)
; #define PG8_MMA(ai, bj, At, Bt) do { __builtin_amdgcn_s_setprio(1); _Pragma("unroll") for (int m = 0; m < 4; ++m) _Pragma("unroll") for (int n = 0; n < 2; ++n) _Pragma("unroll") for (int k = 0; k < 2; ++k) \
;         acc[ai][bj][m][n] = __builtin_amdgcn_mfma_f32_16x16x32_bf16(Bt[n][k], At[m][k], acc[ai][bj][m][n], 0, 0, 0); __builtin_amdgcn_s_setprio(0); } while (0)
; #define PG8_WAIT_V(n) asm volatile("s_waitcnt vmcnt(" #n ")" ::: "memory")
; #define PG8_WAIT_L(n) asm volatile("s_waitcnt lgkmcnt(" #n ")" ::: "memory")
; #define PG8_BAR __builtin_amdgcn_s_barrier()
; #define PG8_SCHED __builtin_amdgcn_sched_barrier(0)
; template <class Epi, class Sched, bool ALIGN_EPI = false, bool SP2 = false>
; __device__ __forceinline__ void gemm_phase(PG8_LAS unsigned char* lds, const Gemm g, const Sched& S, const Epi& E) {
;     ...
;         for (int t = 0; t < nt; t += 2) {
;             const bool last = (t == nt - 2);
;             const char* a1 = cA + (size_t)(t + 1) * kstep;
;             const char* a2 = last ? nA : cA + (size_t)(t + 2) * kstep; const char* b2 = last ? nB : cB + (size_t)(t + 2) * kstep;
;             const char* a3 = a2 + kstep; const char* b3 = b2 + kstep;
;             if (last && has_next) S.a_ready(nxt);
;             if constexpr (SP2) {
;             PG8_LDB(B0, 0, 0); PG8_LDB(B1, 0, 1); PG8_SCHED; PG8_LDA(At, 0, 0); PG8_STAGE(PG8_SA(1, 1), a1 + hstep, voffA);
;             PG8_WAIT_V(8); PG8_WAIT_L(0); PG8_BAR; PG8_MMA(0, 0, At, B0); PG8_MMA(0, 1, At, B1); PG8_BAR; PG8_SCHED;
.LBB0_328:
	s_ashr_i32 s17, s16, 31
	s_lshl_b64 s[20:21], s[16:17], 19
	s_add_u32 s20, s37, s20
	s_addc_u32 s21, s38, s21
	s_and_b64 s[22:23], s[6:7], exec
	s_cselect_b32 s3, s21, s29
	s_cselect_b32 s17, s20, s28
	s_ashr_i32 s19, s18, 31
	s_lshl_b64 s[22:23], s[18:19], 19
	s_add_u32 s22, s39, s22
	s_addc_u32 s23, s40, s23
	s_and_b64 s[34:35], s[6:7], exec
	s_cselect_b32 s19, s23, s31
	s_cselect_b32 s25, s22, s30
	s_add_u32 s28, s28, 0x40080
	s_addc_u32 s29, s29, 0
	s_add_u32 s27, s30, 0x100
	s_addc_u32 s44, s31, 0
	s_mov_b32 s45, -2
	s_add_u32 s30, s28, 0xfffc0080
	s_addc_u32 s31, s29, -1
	s_cmp_eq_u32 s45, 12
	s_cselect_b32 s35, s3, s31
	s_cselect_b32 s34, s17, s30
	s_cselect_b32 s31, s19, s44
	s_cselect_b32 s30, s25, s27
	ds_read_b128 v[108:111], v251
	ds_read_b128 v[112:115], v251 offset:1024
	ds_read_b128 v[124:127], v251 offset:2048
	ds_read_b128 v[128:131], v251 offset:3072
	ds_read_b128 v[132:135], v251 offset:16384
	ds_read_b128 v[140:143], v251 offset:17408
	ds_read_b128 v[148:151], v251 offset:18432
	ds_read_b128 v[156:159], v251 offset:19456
	v_lshl_add_u64 v[212:213], s[28:29], 0, v[208:209]
	s_add_i32 m0, s42, 0xc000
	ds_read_b128 v[164:167], v253
	ds_read_b128 v[168:171], v253 offset:1024
	ds_read_b128 v[172:175], v253 offset:2048
	ds_read_b128 v[176:179], v253 offset:3072
	ds_read_b128 v[180:183], v253 offset:4096
	ds_read_b128 v[184:187], v253 offset:5120
	ds_read_b128 v[188:191], v253 offset:6144
	ds_read_b128 v[192:195], v253 offset:7168
	global_load_lds_dwordx4 v[212:213], off
	s_add_i32 m0, s42, 0xe000
	v_lshl_add_u64 v[212:213], s[28:29], 0, v[210:211]
	global_load_lds_dwordx4 v[212:213], off
	s_waitcnt vmcnt(8) lgkmcnt(0)
	s_barrier
	s_setprio 1
	v_mfma_f32_16x16x32_bf16 v[160:163], v[108:111], v[164:167], 0
	v_mfma_f32_16x16x32_bf16 v[152:155], v[124:127], v[164:167], 0
	v_mfma_f32_16x16x32_bf16 v[120:123], v[108:111], v[172:175], 0
	v_mfma_f32_16x16x32_bf16 v[116:119], v[124:127], v[172:175], 0
	v_mfma_f32_16x16x32_bf16 v[96:99], v[108:111], v[180:183], 0
	v_mfma_f32_16x16x32_bf16 v[92:95], v[124:127], v[180:183], 0
	v_mfma_f32_16x16x32_bf16 v[80:83], v[108:111], v[188:191], 0
	v_mfma_f32_16x16x32_bf16 v[76:79], v[124:127], v[188:191], 0
	v_mfma_f32_16x16x32_bf16 v[160:163], v[112:115], v[168:171], v[160:163]
	v_mfma_f32_16x16x32_bf16 v[152:155], v[128:131], v[168:171], v[152:155]
	v_mfma_f32_16x16x32_bf16 v[120:123], v[112:115], v[176:179], v[120:123]
	v_mfma_f32_16x16x32_bf16 v[116:119], v[128:131], v[176:179], v[116:119]
	v_mfma_f32_16x16x32_bf16 v[96:99], v[112:115], v[184:187], v[96:99]
	v_mfma_f32_16x16x32_bf16 v[92:95], v[128:131], v[184:187], v[92:95]
	v_mfma_f32_16x16x32_bf16 v[80:83], v[112:115], v[192:195], v[80:83]
	v_mfma_f32_16x16x32_bf16 v[76:79], v[128:131], v[192:195], v[76:79]
	s_setprio 0
	s_setprio 1
	v_mfma_f32_16x16x32_bf16 v[144:147], v[132:135], v[164:167], 0
	v_mfma_f32_16x16x32_bf16 v[136:139], v[148:151], v[164:167], 0
	v_mfma_f32_16x16x32_bf16 v[104:107], v[132:135], v[172:175], 0
	v_mfma_f32_16x16x32_bf16 v[100:103], v[148:151], v[172:175], 0
	v_mfma_f32_16x16x32_bf16 v[88:91], v[132:135], v[180:183], 0
	v_mfma_f32_16x16x32_bf16 v[84:87], v[148:151], v[180:183], 0
	v_mfma_f32_16x16x32_bf16 v[72:75], v[132:135], v[188:191], 0
	v_mfma_f32_16x16x32_bf16 v[68:71], v[148:151], v[188:191], 0
	v_mfma_f32_16x16x32_bf16 v[144:147], v[140:143], v[168:171], v[144:147]
	v_mfma_f32_16x16x32_bf16 v[136:139], v[156:159], v[168:171], v[136:139]
	v_mfma_f32_16x16x32_bf16 v[104:107], v[140:143], v[176:179], v[104:107]
	v_mfma_f32_16x16x32_bf16 v[100:103], v[156:159], v[176:179], v[100:103]
	v_mfma_f32_16x16x32_bf16 v[88:91], v[140:143], v[184:187], v[88:91]
	v_mfma_f32_16x16x32_bf16 v[84:87], v[156:159], v[184:187], v[84:87]
	v_mfma_f32_16x16x32_bf16 v[72:75], v[140:143], v[192:195], v[72:75]
	v_mfma_f32_16x16x32_bf16 v[68:71], v[156:159], v[192:195], v[68:71]
	s_setprio 0
	s_barrier
; #define PG8_STAGE(bufoff, gbase, voff) do { _Pragma("unroll") for (int _i = 0; _i < 2; ++_i) \
;         __builtin_amdgcn_global_load_lds((const unsigned*)((const char*)(gbase) + (voff)[_i]), (PG8_LAS unsigned*)(lds + (bufoff) + ldsw + _i * 8192), 16, 0, 0); } while (0)
; #define PG8_LDA(dst, b, h) do { _Pragma("unroll") for (int m = 0; m < 4; ++m) _Pragma("unroll") for (int k = 0; k < 2; ++k) dst[m][k] = *(const PG8_LAS bf16x8*)(lds + PG8_SA(b, h) + aoff + m * 2048 + k * 1024); } while (0)
; #define PG8_MMA(ai, bj, At, Bt) do { __builtin_amdgcn_s_setprio(1); _Pragma("unroll") for (int m = 0; m < 4; ++m) _Pragma("unroll") for (int n = 0; n < 2; ++n) _Pragma("unroll") for (int k = 0; k < 2; ++k) \
;         acc[ai][bj][m][n] = __builtin_amdgcn_mfma_f32_16x16x32_bf16(Bt[n][k], At[m][k], acc[ai][bj][m][n], 0, 0, 0); __builtin_amdgcn_s_setprio(0); } while (0)
; #define PG8_WAIT_V(n) asm volatile("s_waitcnt vmcnt(" #n ")" ::: "memory")
; #define PG8_WAIT_L(n) asm volatile("s_waitcnt lgkmcnt(" #n ")" ::: "memory")
; #define PG8_BAR __builtin_amdgcn_s_barrier()
; #define PG8_SCHED __builtin_amdgcn_sched_barrier(0)
; template <class Epi, class Sched, bool ALIGN_EPI = false, bool SP2 = false>
; __device__ __forceinline__ void gemm_phase(PG8_LAS unsigned char* lds, const Gemm g, const Sched& S, const Epi& E) {
;     ...
;             PG8_LDA(At, 0, 1); PG8_STAGE(PG8_SB(0, 0), b2, voffB); PG8_STAGE(PG8_SB(0, 1), b2 + hstep, voffB); PG8_STAGE(PG8_SA(0, 0), a2, voffA);
;             PG8_WAIT_V(8); PG8_WAIT_L(0); PG8_BAR; PG8_MMA(1, 0, At, B0); PG8_MMA(1, 1, At, B1); PG8_BAR; PG8_SCHED;
	v_lshl_add_u64 v[212:213], s[30:31], 0, v[202:203]
	s_add_i32 m0, s41, 0x10000
	ds_read_b128 v[164:167], v253 offset:16384
	ds_read_b128 v[168:171], v253 offset:17408
	ds_read_b128 v[172:175], v253 offset:18432
	ds_read_b128 v[176:179], v253 offset:19456
	ds_read_b128 v[180:183], v253 offset:20480
	ds_read_b128 v[184:187], v253 offset:21504
	ds_read_b128 v[188:191], v253 offset:22528
	ds_read_b128 v[192:195], v253 offset:23552
	global_load_lds_dwordx4 v[212:213], off
	s_add_i32 m0, s41, 0x12000
	s_add_u32 s52, s30, 0x40000
	v_lshl_add_u64 v[214:215], s[30:31], 0, v[206:207]
	s_addc_u32 s53, s31, 0
	global_load_lds_dwordx4 v[214:215], off
	v_lshl_add_u64 v[216:217], s[52:53], 0, v[202:203]
	s_add_i32 m0, s41, 0x14000
	v_lshl_add_u64 v[218:219], s[34:35], 0, v[204:205]
	global_load_lds_dwordx4 v[216:217], off
	s_add_i32 m0, s41, 0x16000
	v_lshl_add_u64 v[216:217], s[52:53], 0, v[206:207]
	global_load_lds_dwordx4 v[216:217], off
	s_mov_b32 m0, s42
	v_lshl_add_u64 v[216:217], s[34:35], 0, v[0:1]
	global_load_lds_dwordx4 v[216:217], off
	s_mov_b32 m0, s43
	s_add_i32 s52, 0, 0x18000
	global_load_lds_dwordx4 v[218:219], off
	s_waitcnt vmcnt(8) lgkmcnt(0)
	s_barrier
	s_setprio 1
	v_mfma_f32_16x16x32_bf16 v[64:67], v[108:111], v[164:167], 0
	v_mfma_f32_16x16x32_bf16 v[60:63], v[124:127], v[164:167], 0
	v_mfma_f32_16x16x32_bf16 v[48:51], v[108:111], v[172:175], 0
	v_mfma_f32_16x16x32_bf16 v[44:47], v[124:127], v[172:175], 0
	v_mfma_f32_16x16x32_bf16 v[32:35], v[108:111], v[180:183], 0
	v_mfma_f32_16x16x32_bf16 v[28:31], v[124:127], v[180:183], 0
	v_mfma_f32_16x16x32_bf16 v[16:19], v[108:111], v[188:191], 0
	v_mfma_f32_16x16x32_bf16 v[12:15], v[124:127], v[188:191], 0
	v_mfma_f32_16x16x32_bf16 v[64:67], v[112:115], v[168:171], v[64:67]
	v_mfma_f32_16x16x32_bf16 v[60:63], v[128:131], v[168:171], v[60:63]
	v_mfma_f32_16x16x32_bf16 v[48:51], v[112:115], v[176:179], v[48:51]
	v_mfma_f32_16x16x32_bf16 v[44:47], v[128:131], v[176:179], v[44:47]
	v_mfma_f32_16x16x32_bf16 v[32:35], v[112:115], v[184:187], v[32:35]
	v_mfma_f32_16x16x32_bf16 v[28:31], v[128:131], v[184:187], v[28:31]
	v_mfma_f32_16x16x32_bf16 v[16:19], v[112:115], v[192:195], v[16:19]
	v_mfma_f32_16x16x32_bf16 v[12:15], v[128:131], v[192:195], v[12:15]
	s_setprio 0
	s_setprio 1
	v_mfma_f32_16x16x32_bf16 v[56:59], v[132:135], v[164:167], 0
	v_mfma_f32_16x16x32_bf16 v[52:55], v[148:151], v[164:167], 0
	v_mfma_f32_16x16x32_bf16 v[40:43], v[132:135], v[172:175], 0
	v_mfma_f32_16x16x32_bf16 v[36:39], v[148:151], v[172:175], 0
	v_mfma_f32_16x16x32_bf16 v[24:27], v[132:135], v[180:183], 0
	v_mfma_f32_16x16x32_bf16 v[20:23], v[148:151], v[180:183], 0
	v_mfma_f32_16x16x32_bf16 v[8:11], v[132:135], v[188:191], 0
	v_mfma_f32_16x16x32_bf16 v[4:7], v[148:151], v[188:191], 0
	v_mfma_f32_16x16x32_bf16 v[56:59], v[140:143], v[168:171], v[56:59]
	v_mfma_f32_16x16x32_bf16 v[52:55], v[156:159], v[168:171], v[52:55]
	v_mfma_f32_16x16x32_bf16 v[40:43], v[140:143], v[176:179], v[40:43]
	v_mfma_f32_16x16x32_bf16 v[36:39], v[156:159], v[176:179], v[36:39]
	v_mfma_f32_16x16x32_bf16 v[24:27], v[140:143], v[184:187], v[24:27]
	v_mfma_f32_16x16x32_bf16 v[20:23], v[156:159], v[184:187], v[20:23]
	v_mfma_f32_16x16x32_bf16 v[8:11], v[140:143], v[192:195], v[8:11]
	v_mfma_f32_16x16x32_bf16 v[4:7], v[156:159], v[192:195], v[4:7]
	s_setprio 0
	s_barrier
	s_branch .Lkmid_1

; __device__ __forceinline__ int opaque_tid() { int t = (int)threadIdx.x; asm volatile("" : "+v"(t)); return t; }
; #define PG8_STAGE(bufoff, gbase, voff) do { _Pragma("unroll") for (int _i = 0; _i < 2; ++_i) \
;         __builtin_amdgcn_global_load_lds((const unsigned*)((const char*)(gbase) + (voff)[_i]), (PG8_LAS unsigned*)(lds + (bufoff) + ldsw + _i * 8192), 16, 0, 0); } while (0)
; #define PG8_WAIT_V(n) asm volatile("s_waitcnt vmcnt(" #n ")" ::: "memory")
; #define PG8_BAR __builtin_amdgcn_s_barrier()
; template <class Epi, class Sched, bool ALIGN_EPI = false, bool SP2 = false>
; __device__ __forceinline__ void gemm_phase(PG8_LAS unsigned char* lds, const Gemm g, const Sched& S, const Epi& E) {
;     const int tid = opaque_tid(), wid = __builtin_amdgcn_readfirstlane(tid >> 6), lane = tid & 63, wr = wid >> 2, wc = wid & 3, fr = lane & 15, fq = lane >> 4;
;     const int K = g.K, nt = K / BK;
;     unsigned voffA[2], voffB[2];
; #pragma unroll
;     for (int i = 0; i < 2; ++i) { int R, C; stage_rc(tid * 16 + i * 8192, R, C); const int Rb = Epi::PERM ? ((R & ~31) + perm32(R & 31)) : R;
;         voffA[i] = (unsigned)(R * K + C) * 2u; voffB[i] = (unsigned)(Rb * K + C) * 2u; }
;     const size_t kstep = (size_t)(BK * 2);
;     const size_t hstep = (size_t)HALF * K * 2;
;     const size_t tstep = 2 * hstep;
;     const unsigned ldsw = (unsigned)wid * 1024u;
;     const int aoff = lds_byte(wr * 64 + fr, fq * 8), boff = lds_byte(wc * 32 + fr, fq * 8);
;     ...
;         PG8_STAGE(PG8_SB(1, 0), cB + kstep, voffB); PG8_STAGE(PG8_SA(1, 0), cA + kstep, voffA); PG8_STAGE(PG8_SB(1, 1), cB + hstep + kstep, voffB);
;         PG8_WAIT_V(6); PG8_BAR;
.LBB0_466:
	s_add_u32 s18, s14, 0x6400000
	s_addc_u32 s19, s15, 0
	s_add_u32 s14, s14, 0x1a400000
	s_addc_u32 s15, s15, 0
	s_and_b32 s46, s5, 3
	s_add_i32 m0, s40, 0x18000
	v_lshl_add_u64 v[10:11], v[10:11], 0, s[82:83]
	s_lshl_b32 s5, s4, 13
	s_lshl_b32 s9, s46, 12
	s_waitcnt vmcnt(2)
	s_barrier
	global_load_lds_dwordx4 v[10:11], off
	v_lshl_add_u64 v[8:9], v[8:9], 0, s[82:83]
	s_add_i32 m0, s40, 0x1a000
	s_add_i32 s47, s40, 0x8000
	s_add_i32 s48, s40, 0xa000
	global_load_lds_dwordx4 v[8:9], off
	v_lshl_add_u64 v[4:5], v[4:5], 0, s[82:83]
	s_mov_b32 m0, s47
	s_add_u32 s6, s28, 0xb0080
	global_load_lds_dwordx4 v[4:5], off
	v_lshl_add_u64 v[4:5], v[6:7], 0, s[82:83]
	s_mov_b32 m0, s48
	s_addc_u32 s7, s29, 0
	global_load_lds_dwordx4 v[4:5], off
	s_add_i32 m0, s40, 0x1c000
	v_lshl_add_u64 v[4:5], s[6:7], 0, v[192:193]
	global_load_lds_dwordx4 v[4:5], off
	v_lshl_add_u64 v[4:5], s[6:7], 0, v[202:203]
	s_add_i32 m0, s40, 0x1e000
	s_mov_b32 s1, 0xb000
	global_load_lds_dwordx4 v[4:5], off
	v_bfe_u32 v4, v12, 4, 2
	v_and_b32_e32 v5, 15, v12
	v_lshlrev_b32_e32 v7, 4, v4
	v_lshl_or_b32 v3, s4, 6, v5
	v_lshl_or_b32 v5, v5, 6, v7
	v_lshlrev_b32_e32 v7, 2, v12
	v_and_b32_e32 v7, 32, v7
	v_lshlrev_b32_e32 v6, 3, v4
	v_bitop3_b32 v8, v5, s5, v7 bitop3:0xde
	v_bitop3_b32 v234, v5, s9, v7 bitop3:0xde
	v_add_u32_e32 v234, 0x10000, v234
	v_cmp_eq_u32_e64 s[4:5], 0, v4
	v_lshrrev_b32_e32 v5, 1, v13
	v_mul_lo_u32 v4, v15, s77
	v_mad_u64_u32 v[4:5], s[6:7], v5, s1, v[4:5]
	v_or_b32_e32 v4, v4, v14
	s_cmpk_lt_u32 s8, 0x100
	v_add_lshl_u32 v4, v4, v16, 1
	v_mov_b32_e32 v5, v2
	s_mov_b64 s[8:9], 0xb0080
	v_lshl_add_u64 v[204:205], v[4:5], 0, s[8:9]
	v_lshrrev_b32_e32 v5, 1, v17
	v_mul_lo_u32 v4, v19, s77
	v_mad_u64_u32 v[4:5], s[6:7], v5, s1, v[4:5]
	s_waitcnt vmcnt(6)
	v_or_b32_e32 v4, v4, v18
	v_add_lshl_u32 v4, v4, v20, 1
	v_mov_b32_e32 v5, v2
	v_lshl_or_b32 v235, s46, 5, v6
	s_cselect_b64 s[20:21], -1, 0
	s_mov_b32 s72, 0
	s_ashr_i32 s49, s34, 31
	v_lshl_add_u64 v[206:207], v[4:5], 0, s[8:9]
	v_add_u32_e32 v236, 0, v8
	s_waitcnt vmcnt(0)
	s_barrier
	s_branch .LBB0_469

; #define PG8_STAGE(bufoff, gbase, voff) do { _Pragma("unroll") for (int _i = 0; _i < 2; ++_i) \
;         __builtin_amdgcn_global_load_lds((const unsigned*)((const char*)(gbase) + (voff)[_i]), (PG8_LAS unsigned*)(lds + (bufoff) + ldsw + _i * 8192), 16, 0, 0); } while (0)
; #define PG8_LDA(dst, b, h) do { _Pragma("unroll") for (int m = 0; m < 4; ++m) _Pragma("unroll") for (int k = 0; k < 2; ++k) dst[m][k] = *(const PG8_LAS bf16x8*)(lds + PG8_SA(b, h) + aoff + m * 2048 + k * 1024); } while (0)
; #define PG8_LDB(dst, b, h) do { _Pragma("unroll") for (int n = 0; n < 2; ++n) _Pragma("unroll") for (int k = 0; k < 2; ++k) dst[n][k] = *(const PG8_LAS bf16x8*)(lds + PG8_SB(b, h) + boff + n * 2048 + k * 1024); } while (0)
; #define PG8_MMA(ai, bj, At, Bt) do { __builtin_amdgcn_s_setprio(1); _Pragma("unroll") for (int m = 0; m < 4; ++m) _Pragma("unroll") for (int n = 0; n < 2; ++n) _Pragma("unroll") for (int k = 0; k < 2; ++k) \
;         acc[ai][bj][m][n] = __builtin_amdgcn_mfma_f32_16x16x32_bf16(Bt[n][k], At[m][k], acc[ai][bj][m][n], 0, 0, 0); __builtin_amdgcn_s_setprio(0); } while (0)
; #define PG8_WAIT_V(n) asm volatile("s_waitcnt vmcnt(" #n ")" ::: "memory")
; #define PG8_BAR __builtin_amdgcn_s_barrier()
; template <class Epi, class Sched, bool ALIGN_EPI = false, bool SP2 = false>
; __device__ __forceinline__ void gemm_phase(PG8_LAS unsigned char* lds, const Gemm g, const Sched& S, const Epi& E) {
;     ...
;         for (int t = 0; t < nt; t += 2) {
;             const bool last = (t == nt - 2);
;             const char* a1 = cA + (size_t)(t + 1) * kstep;
;             const char* a2 = last ? nA : cA + (size_t)(t + 2) * kstep; const char* b2 = last ? nB : cB + (size_t)(t + 2) * kstep;
;             const char* a3 = a2 + kstep; const char* b3 = b2 + kstep;
;             if (last && has_next) S.a_ready(nxt);
;             if constexpr (SP2) {
;             PG8_LDB(B0, 0, 0); PG8_LDB(B1, 0, 1); PG8_SCHED; PG8_LDA(At, 0, 0); PG8_STAGE(PG8_SA(1, 1), a1 + hstep, voffA);
;             PG8_WAIT_V(8); PG8_WAIT_L(0); PG8_BAR; PG8_MMA(0, 0, At, B0); PG8_MMA(0, 1, At, B1); PG8_BAR; PG8_SCHED;
;             PG8_LDA(At, 0, 1); PG8_STAGE(PG8_SB(0, 0), b2, voffB); PG8_STAGE(PG8_SB(0, 1), b2 + hstep, voffB); PG8_STAGE(PG8_SA(0, 0), a2, voffA);
;             PG8_WAIT_V(8); PG8_WAIT_L(0); PG8_BAR; PG8_MMA(1, 0, At, B0); PG8_MMA(1, 1, At, B1); PG8_BAR; PG8_SCHED;
.LBB0_479:
	s_add_u32 s44, s28, 0x100
	s_addc_u32 s45, s29, 0
	s_mov_b32 s53, -2
	s_add_u32 s8, s26, 0x100
	s_addc_u32 s9, s27, 0
	s_cmp_eq_u32 s53, 40
	s_cselect_b32 s31, s23, s9
	s_cselect_b32 s30, s22, s8
	s_cselect_b32 s29, s25, s45
	s_cselect_b32 s28, s24, s44
	ds_read_b128 v[68:71], v234
	ds_read_b128 v[80:83], v234 offset:1024
	ds_read_b128 v[92:95], v234 offset:2048
	ds_read_b128 v[100:103], v234 offset:3072
	ds_read_b128 v[112:115], v234 offset:16384
	ds_read_b128 v[120:123], v234 offset:17408
	ds_read_b128 v[132:135], v234 offset:18432
	ds_read_b128 v[144:147], v234 offset:19456
	v_lshl_add_u64 v[198:199], s[26:27], 0, v[204:205]
	s_add_i32 m0, s40, 0xc000
	ds_read_b128 v[156:159], v236
	ds_read_b128 v[168:171], v236 offset:1024
	ds_read_b128 v[172:175], v236 offset:2048
	ds_read_b128 v[176:179], v236 offset:3072
	ds_read_b128 v[180:183], v236 offset:4096
	ds_read_b128 v[184:187], v236 offset:5120
	ds_read_b128 v[188:191], v236 offset:6144
	ds_read_b128 v[208:211], v236 offset:7168
	global_load_lds_dwordx4 v[198:199], off
	s_add_i32 m0, s40, 0xe000
	v_lshl_add_u64 v[198:199], s[26:27], 0, v[206:207]
	global_load_lds_dwordx4 v[198:199], off
	s_waitcnt vmcnt(8) lgkmcnt(0)
	s_barrier
	s_setprio 1
	v_mfma_f32_16x16x32_bf16 v[164:167], v[68:71], v[156:159], 0
	v_mfma_f32_16x16x32_bf16 v[160:163], v[92:95], v[156:159], 0
	v_mfma_f32_16x16x32_bf16 v[140:143], v[68:71], v[172:175], 0
	v_mfma_f32_16x16x32_bf16 v[136:139], v[92:95], v[172:175], 0
	v_mfma_f32_16x16x32_bf16 v[116:119], v[68:71], v[180:183], 0
	v_mfma_f32_16x16x32_bf16 v[108:111], v[92:95], v[180:183], 0
	v_mfma_f32_16x16x32_bf16 v[88:91], v[68:71], v[188:191], 0
	v_mfma_f32_16x16x32_bf16 v[84:87], v[92:95], v[188:191], 0
	v_mfma_f32_16x16x32_bf16 v[164:167], v[80:83], v[168:171], v[164:167]
	v_mfma_f32_16x16x32_bf16 v[160:163], v[100:103], v[168:171], v[160:163]
	v_mfma_f32_16x16x32_bf16 v[140:143], v[80:83], v[176:179], v[140:143]
	v_mfma_f32_16x16x32_bf16 v[136:139], v[100:103], v[176:179], v[136:139]
	v_mfma_f32_16x16x32_bf16 v[116:119], v[80:83], v[184:187], v[116:119]
	v_mfma_f32_16x16x32_bf16 v[108:111], v[100:103], v[184:187], v[108:111]
	v_mfma_f32_16x16x32_bf16 v[88:91], v[80:83], v[208:211], v[88:91]
	v_mfma_f32_16x16x32_bf16 v[84:87], v[100:103], v[208:211], v[84:87]
	s_setprio 0
	s_setprio 1
	v_mfma_f32_16x16x32_bf16 v[152:155], v[112:115], v[156:159], 0
	v_mfma_f32_16x16x32_bf16 v[148:151], v[132:135], v[156:159], 0
	v_mfma_f32_16x16x32_bf16 v[128:131], v[112:115], v[172:175], 0
	v_mfma_f32_16x16x32_bf16 v[124:127], v[132:135], v[172:175], 0
	v_mfma_f32_16x16x32_bf16 v[104:107], v[112:115], v[180:183], 0
	v_mfma_f32_16x16x32_bf16 v[96:99], v[132:135], v[180:183], 0
	v_mfma_f32_16x16x32_bf16 v[76:79], v[112:115], v[188:191], 0
	v_mfma_f32_16x16x32_bf16 v[72:75], v[132:135], v[188:191], 0
	v_mfma_f32_16x16x32_bf16 v[152:155], v[120:123], v[168:171], v[152:155]
	v_mfma_f32_16x16x32_bf16 v[148:151], v[144:147], v[168:171], v[148:151]
	v_mfma_f32_16x16x32_bf16 v[128:131], v[120:123], v[176:179], v[128:131]
	v_mfma_f32_16x16x32_bf16 v[124:127], v[144:147], v[176:179], v[124:127]
	v_mfma_f32_16x16x32_bf16 v[104:107], v[120:123], v[184:187], v[104:107]
	v_mfma_f32_16x16x32_bf16 v[96:99], v[144:147], v[184:187], v[96:99]
	v_mfma_f32_16x16x32_bf16 v[76:79], v[120:123], v[208:211], v[76:79]
	v_mfma_f32_16x16x32_bf16 v[72:75], v[144:147], v[208:211], v[72:75]
	s_setprio 0
	s_barrier
	v_lshl_add_u64 v[198:199], s[28:29], 0, v[192:193]
	s_add_i32 m0, s39, 0x10000
	ds_read_b128 v[156:159], v236 offset:16384
	ds_read_b128 v[168:171], v236 offset:17408
	ds_read_b128 v[172:175], v236 offset:18432
	ds_read_b128 v[176:179], v236 offset:19456
	ds_read_b128 v[180:183], v236 offset:20480
	ds_read_b128 v[184:187], v236 offset:21504
	ds_read_b128 v[188:191], v236 offset:22528
	ds_read_b128 v[208:211], v236 offset:23552
	global_load_lds_dwordx4 v[198:199], off
	s_add_i32 m0, s39, 0x12000
	s_add_u32 s26, s28, 0xb0000
	v_lshl_add_u64 v[212:213], s[28:29], 0, v[202:203]
	s_addc_u32 s27, s29, 0
	global_load_lds_dwordx4 v[212:213], off
	v_lshl_add_u64 v[214:215], s[26:27], 0, v[192:193]
	s_add_i32 m0, s39, 0x14000
	v_lshl_add_u64 v[216:217], s[30:31], 0, v[194:195]
	global_load_lds_dwordx4 v[214:215], off
	s_add_i32 m0, s39, 0x16000
	v_lshl_add_u64 v[214:215], s[26:27], 0, v[202:203]
	global_load_lds_dwordx4 v[214:215], off
	s_mov_b32 m0, s40
	v_lshl_add_u64 v[214:215], s[30:31], 0, v[0:1]
	global_load_lds_dwordx4 v[214:215], off
	s_mov_b32 m0, s41
	s_add_i32 s54, 0, 0x18000
	global_load_lds_dwordx4 v[216:217], off
	s_waitcnt vmcnt(8) lgkmcnt(0)
	s_barrier
	s_setprio 1
	v_mfma_f32_16x16x32_bf16 v[64:67], v[68:71], v[156:159], 0
	v_mfma_f32_16x16x32_bf16 v[60:63], v[92:95], v[156:159], 0
	v_mfma_f32_16x16x32_bf16 v[48:51], v[68:71], v[172:175], 0
	v_mfma_f32_16x16x32_bf16 v[44:47], v[92:95], v[172:175], 0
	v_mfma_f32_16x16x32_bf16 v[32:35], v[68:71], v[180:183], 0
	v_mfma_f32_16x16x32_bf16 v[28:31], v[92:95], v[180:183], 0
	v_mfma_f32_16x16x32_bf16 v[16:19], v[68:71], v[188:191], 0
	v_mfma_f32_16x16x32_bf16 v[12:15], v[92:95], v[188:191], 0
	v_mfma_f32_16x16x32_bf16 v[64:67], v[80:83], v[168:171], v[64:67]
	v_mfma_f32_16x16x32_bf16 v[60:63], v[100:103], v[168:171], v[60:63]
	v_mfma_f32_16x16x32_bf16 v[48:51], v[80:83], v[176:179], v[48:51]
	v_mfma_f32_16x16x32_bf16 v[44:47], v[100:103], v[176:179], v[44:47]
	v_mfma_f32_16x16x32_bf16 v[32:35], v[80:83], v[184:187], v[32:35]
	v_mfma_f32_16x16x32_bf16 v[28:31], v[100:103], v[184:187], v[28:31]
	v_mfma_f32_16x16x32_bf16 v[16:19], v[80:83], v[208:211], v[16:19]
	v_mfma_f32_16x16x32_bf16 v[12:15], v[100:103], v[208:211], v[12:15]
	s_setprio 0
	s_setprio 1
	v_mfma_f32_16x16x32_bf16 v[56:59], v[112:115], v[156:159], 0
	v_mfma_f32_16x16x32_bf16 v[52:55], v[132:135], v[156:159], 0
	v_mfma_f32_16x16x32_bf16 v[40:43], v[112:115], v[172:175], 0
	v_mfma_f32_16x16x32_bf16 v[36:39], v[132:135], v[172:175], 0
	v_mfma_f32_16x16x32_bf16 v[24:27], v[112:115], v[180:183], 0
	v_mfma_f32_16x16x32_bf16 v[20:23], v[132:135], v[180:183], 0
	v_mfma_f32_16x16x32_bf16 v[8:11], v[112:115], v[188:191], 0
	v_mfma_f32_16x16x32_bf16 v[4:7], v[132:135], v[188:191], 0
	v_mfma_f32_16x16x32_bf16 v[56:59], v[120:123], v[168:171], v[56:59]
	v_mfma_f32_16x16x32_bf16 v[52:55], v[144:147], v[168:171], v[52:55]
	v_mfma_f32_16x16x32_bf16 v[40:43], v[120:123], v[176:179], v[40:43]
	v_mfma_f32_16x16x32_bf16 v[36:39], v[144:147], v[176:179], v[36:39]
	v_mfma_f32_16x16x32_bf16 v[24:27], v[120:123], v[184:187], v[24:27]
	v_mfma_f32_16x16x32_bf16 v[20:23], v[144:147], v[184:187], v[20:23]
	v_mfma_f32_16x16x32_bf16 v[8:11], v[120:123], v[208:211], v[8:11]
	v_mfma_f32_16x16x32_bf16 v[4:7], v[144:147], v[208:211], v[4:7]
	s_setprio 0
	s_barrier
	s_branch .Lkmid_3
